# speedup vs baseline: 1.0016x; 1.0016x over previous
.LBB0_409:
	v_readlane_b32 s100, v254, 62
	s_nop 0
	s_cmp_eq_u32 s100, 3
	s_cselect_b64 s[100:101], 0, -1
	v_mov_b32_e32 v126, v226
	s_lshl_b32 s58, s22, 8
	v_and_b32_e32 v127, 15, v126
	v_bfe_u32 v126, v126, 4, 2
	v_and_b32_e32 v202, 1, v126
	v_mul_u32_u24_e32 v204, 12, v202
	v_mul_u32_u24_e32 v202, 24, v202
	v_mov_b32_e32 v203, 0
	v_mov_b32_e32 v205, 0
	s_mov_b64 s[60:61], -1
	s_and_b64 vcc, exec, s[46:47]
	s_cbranch_vccz .LBB0_411
	s_ashr_i32 s59, s58, 31
	v_readlane_b32 s60, v251, 0
	s_lshl_b64 s[2:3], s[58:59], 13
	v_readlane_b32 s66, v251, 6
	v_readlane_b32 s61, v251, 1
	v_readlane_b32 s67, v251, 7
	s_add_u32 s66, s66, s2
	v_readlane_b32 s62, v251, 2
	v_readlane_b32 s63, v251, 3
	v_readlane_b32 s64, v251, 4
	v_readlane_b32 s65, v251, 5
	s_addc_u32 s67, s67, s3
	s_mov_b64 s[60:61], 0

.LBB0_416:
	v_readlane_b32 s2, v251, 22
	v_readlane_b32 s2, v251, 16
	v_readlane_b32 s3, v251, 17
	v_readlane_b32 s2, v254, 58
	v_readlane_b32 s3, v254, 59
	v_readlane_b32 s72, v251, 0
	s_lshl_b64 s[2:3], s[58:59], 11
	s_lshl_b64 s[60:61], s[58:59], 13
	v_readlane_b32 s78, v251, 6
	v_readlane_b32 s73, v251, 1
	v_readlane_b32 s79, v251, 7
	s_add_u32 s60, s78, s60
	s_addc_u32 s61, s79, s61
	s_lshl_b64 s[62:63], s[58:59], 12
	v_readlane_b32 s72, v253, 22
	v_readlane_b32 s73, v253, 23
	s_add_u32 s62, s72, s62
	s_addc_u32 s63, s73, s63
	s_lshl_b64 s[58:59], s[58:59], 7
	s_add_u32 s22, s64, s58
	s_addc_u32 s49, s65, s59
	s_lshl_b32 s58, s12, 2
	s_ashr_i32 s59, s58, 31
	s_lshl_b64 s[58:59], s[58:59], 2
	s_add_u32 s22, s22, s58
	s_addc_u32 s49, s49, s59
	s_add_u32 s58, s22, s13
	s_addc_u32 s59, s49, 0
	s_add_u32 s64, s81, s2
	v_readlane_b32 s2, v253, 39
	s_addc_u32 s65, s2, s3
	s_lshl_b32 s2, s12, 8
	s_or_b32 s2, s2, s40
	v_lshl_add_u32 v192, v126, 2, s2
	v_add_u32_e32 v210, s1, v127
	v_lshlrev_b32_e32 v127, 2, v127
	v_ashrrev_i32_e32 v193, 31, v192
	v_lshl_add_u32 v127, v126, 6, v127
	v_ashrrev_i32_e32 v211, 31, v210
	v_lshl_add_u64 v[208:209], v[192:193], 2, s[66:67]
	v_xor_b32_e32 v242, 64, v127
	v_xor_b32_e32 v241, 0x80, v127
	v_cmp_eq_u32_e32 vcc, 0, v126
	v_lshlrev_b64 v[126:127], 13, v[210:211]
	v_lshl_add_u64 v[126:127], v[208:209], 0, v[126:127]
	flat_load_dwordx4 v[194:197], v[126:127]
	flat_load_dwordx4 v[186:189], v[126:127] offset:64
	flat_load_dwordx4 v[182:185], v[126:127] offset:512
	flat_load_dwordx4 v[178:181], v[126:127] offset:576
	v_add_u32_e32 v216, 16, v210
	v_ashrrev_i32_e32 v217, 31, v216
	v_lshlrev_b64 v[126:127], 13, v[216:217]
	v_add_u32_e32 v214, 32, v210
	v_lshl_add_u64 v[126:127], v[208:209], 0, v[126:127]
	v_ashrrev_i32_e32 v215, 31, v214
	flat_load_dwordx4 v[174:177], v[126:127]
	flat_load_dwordx4 v[170:173], v[126:127] offset:64
	flat_load_dwordx4 v[166:169], v[126:127] offset:512
	flat_load_dwordx4 v[162:165], v[126:127] offset:576
	v_lshlrev_b64 v[126:127], 13, v[214:215]
	v_add_u32_e32 v212, 48, v210
	v_lshl_add_u64 v[126:127], v[208:209], 0, v[126:127]
	v_ashrrev_i32_e32 v213, 31, v212
	flat_load_dwordx4 v[158:161], v[126:127]
	flat_load_dwordx4 v[154:157], v[126:127] offset:64
	flat_load_dwordx4 v[150:153], v[126:127] offset:512
	flat_load_dwordx4 v[142:145], v[126:127] offset:576
	v_lshlrev_b64 v[126:127], 13, v[212:213]
	v_lshl_add_u64 v[126:127], v[208:209], 0, v[126:127]
	flat_load_dwordx4 v[146:149], v[126:127]
	flat_load_dwordx4 v[138:141], v[126:127] offset:64
	flat_load_dwordx4 v[134:137], v[126:127] offset:512
	s_nop 0
	flat_load_dwordx4 v[126:129], v[126:127] offset:576
	v_lshlrev_b64 v[198:199], 11, v[210:211]
	v_lshl_add_u64 v[198:199], v[198:199], 0, v[192:193]
	v_lshl_add_u64 v[222:223], v[198:199], 2, s[60:61]
	v_lshl_add_u64 v[220:221], v[198:199], 1, s[62:63]
	v_lshl_add_u64 v[218:219], s[64:65], 0, v[198:199]
	v_readlane_b32 s74, v251, 2
	v_readlane_b32 s75, v251, 3
	v_readlane_b32 s76, v251, 4
	v_readlane_b32 s77, v251, 5
	s_waitcnt vmcnt(0) lgkmcnt(0)
	v_pk_add_f32 v[132:133], v[132:133], v[196:197]
	v_pk_add_f32 v[130:131], v[130:131], v[194:195]
	v_mul_f32_e32 v195, v133, v133
	v_mul_f32_e32 v194, v131, v131
	v_fmac_f32_e32 v194, v130, v130
	v_fmac_f32_e32 v195, v132, v132
	global_store_dwordx4 v[222:223], v[130:133], off
	v_add_f32_e32 v196, v194, v195
	v_cvt_pk_bf16_f32 v194, v130, v131
	v_cvt_pk_bf16_f32 v195, v132, v133
	s_mov_b64 exec, s[100:101]
	v_mov_b32_e32 v228, v194
	v_mov_b32_e32 v229, v195
	s_mov_b64 exec, -1
	v_mov_b32_e32 v194, v1
	v_cvt_pk_fp8_f32 v194, v130, v131
	v_pk_add_f32 v[124:125], v[124:125], v[188:189]
	v_pk_add_f32 v[122:123], v[122:123], v[186:187]
	v_mul_f32_e32 v131, v125, v125
	v_cvt_pk_fp8_f32 v194, v132, v133 op_sel:[0,0,1]
	v_mul_f32_e32 v130, v123, v123
	v_fmac_f32_e32 v130, v122, v122
	v_fmac_f32_e32 v131, v124, v124
	v_add_f32_e32 v130, v130, v131
	s_mov_b64 exec, s[100:101]
	v_mov_b32_e32 v244, v194
	s_mov_b64 exec, -1
	global_store_dwordx4 v[222:223], v[122:125], off offset:64
	v_add_f32_e32 v132, v196, v130
	v_cvt_pk_bf16_f32 v130, v122, v123
	v_cvt_pk_bf16_f32 v131, v124, v125
	s_mov_b64 exec, s[100:101]
	v_mov_b32_e32 v230, v130
	v_mov_b32_e32 v231, v131
	v_lshl_add_u64 v[236:237], v[220:221], 0, v[202:203]
	s_nop 0
	v_permlane16_swap_b32_e32 v228, v230
	v_permlane16_swap_b32_e32 v229, v231
	global_store_dwordx4 v[236:237], v[228:231], off
	s_nop 1
	s_mov_b64 exec, -1
	v_mov_b32_e32 v130, v1
	v_cvt_pk_fp8_f32 v130, v122, v123
	v_pk_add_f32 v[120:121], v[120:121], v[184:185]
	v_pk_add_f32 v[118:119], v[118:119], v[182:183]
	v_mul_f32_e32 v123, v121, v121
	v_cvt_pk_fp8_f32 v130, v124, v125 op_sel:[0,0,1]
	v_mul_f32_e32 v122, v119, v119
	v_fmac_f32_e32 v122, v118, v118
	v_fmac_f32_e32 v123, v120, v120
	v_add_f32_e32 v122, v122, v123
	s_mov_b64 exec, s[100:101]
	v_mov_b32_e32 v245, v130
	v_lshl_add_u64 v[238:239], v[218:219], 0, v[204:205]
	s_nop 0
	v_permlane16_swap_b32_e32 v244, v245
	global_store_dwordx2 v[238:239], v[244:245], off
	s_nop 0
	s_mov_b64 exec, -1
	global_store_dwordx4 v[222:223], v[118:121], off offset:512
	v_add_f32_e32 v124, v132, v122
	v_cvt_pk_bf16_f32 v122, v118, v119
	v_cvt_pk_bf16_f32 v123, v120, v121
	s_mov_b64 exec, s[100:101]
	v_mov_b32_e32 v232, v122
	v_mov_b32_e32 v233, v123
	s_mov_b64 exec, -1
	v_mov_b32_e32 v122, v1
	v_cvt_pk_fp8_f32 v122, v118, v119
	v_pk_add_f32 v[116:117], v[116:117], v[180:181]
	v_pk_add_f32 v[114:115], v[114:115], v[178:179]
	v_mul_f32_e32 v119, v117, v117
	v_cvt_pk_fp8_f32 v122, v120, v121 op_sel:[0,0,1]
	v_mul_f32_e32 v118, v115, v115
	v_fmac_f32_e32 v118, v114, v114
	v_fmac_f32_e32 v119, v116, v116
	v_add_f32_e32 v118, v118, v119
	s_mov_b64 exec, s[100:101]
	v_mov_b32_e32 v246, v122
	s_mov_b64 exec, -1
	global_store_dwordx4 v[222:223], v[114:117], off offset:576
	v_add_f32_e32 v120, v124, v118
	v_cvt_pk_bf16_f32 v118, v114, v115
	v_cvt_pk_bf16_f32 v119, v116, v117
	s_mov_b64 exec, s[100:101]
	v_mov_b32_e32 v234, v118
	v_mov_b32_e32 v235, v119
	v_lshl_add_u64 v[236:237], v[220:221], 0, v[202:203]
	s_nop 0
	v_permlane16_swap_b32_e32 v232, v234
	v_permlane16_swap_b32_e32 v233, v235
	global_store_dwordx4 v[236:237], v[232:235], off offset:256
	s_nop 1
	s_mov_b64 exec, -1
	v_mov_b32_e32 v118, v1
	v_cvt_pk_fp8_f32 v118, v114, v115
	ds_bpermute_b32 v114, v242, v120
	v_cvt_pk_fp8_f32 v118, v116, v117 op_sel:[0,0,1]
	s_waitcnt lgkmcnt(0)
	v_add_f32_e32 v114, v120, v114
	ds_bpermute_b32 v115, v241, v114
	s_mov_b64 exec, s[100:101]
	v_mov_b32_e32 v247, v118
	v_lshl_add_u64 v[238:239], v[218:219], 0, v[204:205]
	s_nop 0
	v_permlane16_swap_b32_e32 v246, v247
	global_store_dwordx2 v[238:239], v[246:247], off offset:128
	s_nop 0
	s_mov_b64 exec, -1
	s_and_saveexec_b64 s[66:67], vcc
	s_cbranch_execz .LBB0_418
	v_lshlrev_b32_e32 v116, 5, v210
	v_ashrrev_i32_e32 v117, 31, v116
	v_lshl_add_u64 v[116:117], v[116:117], 2, s[58:59]
	s_waitcnt lgkmcnt(0)
	v_add_f32_e32 v114, v114, v115
	global_store_dword v[116:117], v114, off
.LBB0_418:
	s_or_b64 exec, exec, s[66:67]
	v_pk_add_f32 v[110:111], v[110:111], v[174:175]
	v_mov_b32_e32 v121, v1
	v_cvt_pk_fp8_f32 v121, v110, v111
	s_waitcnt lgkmcnt(0)
	v_lshlrev_b64 v[114:115], 11, v[216:217]
	v_lshl_add_u64 v[114:115], v[114:115], 0, v[192:193]
	v_pk_add_f32 v[112:113], v[112:113], v[176:177]
	v_lshl_add_u64 v[116:117], v[114:115], 2, s[60:61]
	v_mul_f32_e32 v120, v111, v111
	v_mul_f32_e32 v122, v113, v113
	global_store_dwordx4 v[116:117], v[110:113], off
	v_fmac_f32_e32 v120, v110, v110
	v_fmac_f32_e32 v122, v112, v112
	v_cvt_pk_fp8_f32 v121, v112, v113 op_sel:[0,0,1]
	v_cvt_pk_bf16_f32 v110, v110, v111
	v_cvt_pk_bf16_f32 v111, v112, v113
	v_pk_add_f32 v[106:107], v[106:107], v[170:171]
	v_mov_b32_e32 v112, v1
	v_cvt_pk_fp8_f32 v112, v106, v107
	v_pk_add_f32 v[108:109], v[108:109], v[172:173]
	v_lshl_add_u64 v[118:119], v[114:115], 1, s[62:63]
	v_lshl_add_u64 v[114:115], s[64:65], 0, v[114:115]
	v_cvt_pk_fp8_f32 v112, v108, v109 op_sel:[0,0,1]
	s_mov_b64 exec, s[100:101]
	v_mov_b32_e32 v228, v110
	v_mov_b32_e32 v229, v111
	v_mov_b32_e32 v244, v121
	s_mov_b64 exec, -1
	v_mul_f32_e32 v110, v107, v107
	global_store_dwordx4 v[116:117], v[106:109], off offset:64
	v_fmac_f32_e32 v110, v106, v106
	v_mul_f32_e32 v111, v109, v109
	v_cvt_pk_bf16_f32 v106, v106, v107
	v_cvt_pk_bf16_f32 v107, v108, v109
	v_pk_add_f32 v[104:105], v[104:105], v[168:169]
	v_pk_add_f32 v[102:103], v[102:103], v[166:167]
	v_fmac_f32_e32 v111, v108, v108
	s_mov_b64 exec, s[100:101]
	v_mov_b32_e32 v230, v106
	v_mov_b32_e32 v231, v107
	v_lshl_add_u64 v[236:237], v[118:119], 0, v[202:203]
	s_nop 0
	v_permlane16_swap_b32_e32 v228, v230
	v_permlane16_swap_b32_e32 v229, v231
	global_store_dwordx4 v[236:237], v[228:231], off
	s_nop 1
	v_mov_b32_e32 v245, v112
	v_lshl_add_u64 v[238:239], v[114:115], 0, v[204:205]
	s_nop 0
	v_permlane16_swap_b32_e32 v244, v245
	global_store_dwordx2 v[238:239], v[244:245], off
	s_nop 0
	s_mov_b64 exec, -1
	v_mul_f32_e32 v106, v103, v103
	v_mul_f32_e32 v107, v105, v105
	v_add_f32_e32 v120, v120, v122
	v_add_f32_e32 v110, v110, v111
	v_fmac_f32_e32 v106, v102, v102
	v_fmac_f32_e32 v107, v104, v104
	v_add_f32_e32 v110, v120, v110
	v_add_f32_e32 v106, v106, v107
	v_mov_b32_e32 v108, v1
	global_store_dwordx4 v[116:117], v[102:105], off offset:512
	v_cvt_pk_fp8_f32 v108, v102, v103
	v_add_f32_e32 v109, v110, v106
	v_cvt_pk_bf16_f32 v106, v102, v103
	v_pk_add_f32 v[102:103], v[100:101], v[164:165]
	v_pk_add_f32 v[100:101], v[98:99], v[162:163]
	v_mul_f32_e32 v99, v103, v103
	v_mul_f32_e32 v98, v101, v101
	v_fmac_f32_e32 v98, v100, v100
	v_fmac_f32_e32 v99, v102, v102
	v_add_f32_e32 v98, v98, v99
	v_add_f32_e32 v98, v109, v98
	ds_bpermute_b32 v99, v242, v98
	v_cvt_pk_bf16_f32 v107, v104, v105
	v_cvt_pk_fp8_f32 v108, v104, v105 op_sel:[0,0,1]
	v_mov_b32_e32 v104, v1
	v_cvt_pk_fp8_f32 v104, v100, v101
	s_waitcnt lgkmcnt(0)
	v_add_f32_e32 v98, v98, v99
	ds_bpermute_b32 v99, v241, v98
	s_mov_b64 exec, s[100:101]
	v_mov_b32_e32 v232, v106
	v_mov_b32_e32 v233, v107
	v_mov_b32_e32 v246, v108
	s_mov_b64 exec, -1
	global_store_dwordx4 v[116:117], v[100:103], off offset:576
	v_cvt_pk_fp8_f32 v104, v102, v103 op_sel:[0,0,1]
	s_nop 0
	v_cvt_pk_bf16_f32 v100, v100, v101
	v_cvt_pk_bf16_f32 v101, v102, v103
	s_mov_b64 exec, s[100:101]
	v_mov_b32_e32 v234, v100
	v_mov_b32_e32 v235, v101
	v_lshl_add_u64 v[236:237], v[118:119], 0, v[202:203]
	s_nop 0
	v_permlane16_swap_b32_e32 v232, v234
	v_permlane16_swap_b32_e32 v233, v235
	global_store_dwordx4 v[236:237], v[232:235], off offset:256
	s_nop 1
	v_mov_b32_e32 v247, v104
	v_lshl_add_u64 v[238:239], v[114:115], 0, v[204:205]
	s_nop 0
	v_permlane16_swap_b32_e32 v246, v247
	global_store_dwordx2 v[238:239], v[246:247], off offset:128
	s_nop 0
	s_mov_b64 exec, -1
	s_and_saveexec_b64 s[66:67], vcc
	s_cbranch_execz .LBB0_420
	v_lshlrev_b32_e32 v100, 5, v216
	v_ashrrev_i32_e32 v101, 31, v100
	v_lshl_add_u64 v[100:101], v[100:101], 2, s[58:59]
	s_waitcnt lgkmcnt(0)
	v_add_f32_e32 v98, v98, v99
	global_store_dword v[100:101], v98, off
.LBB0_420:
	s_or_b64 exec, exec, s[66:67]
	v_pk_add_f32 v[94:95], v[94:95], v[158:159]
	v_mov_b32_e32 v105, v1
	v_cvt_pk_fp8_f32 v105, v94, v95
	s_waitcnt lgkmcnt(0)
	v_lshlrev_b64 v[98:99], 11, v[214:215]
	v_lshl_add_u64 v[98:99], v[98:99], 0, v[192:193]
	v_pk_add_f32 v[96:97], v[96:97], v[160:161]
	v_lshl_add_u64 v[100:101], v[98:99], 2, s[60:61]
	v_mul_f32_e32 v104, v95, v95
	v_mul_f32_e32 v106, v97, v97
	global_store_dwordx4 v[100:101], v[94:97], off
	v_fmac_f32_e32 v104, v94, v94
	v_fmac_f32_e32 v106, v96, v96
	v_cvt_pk_fp8_f32 v105, v96, v97 op_sel:[0,0,1]
	v_cvt_pk_bf16_f32 v94, v94, v95
	v_cvt_pk_bf16_f32 v95, v96, v97
	v_pk_add_f32 v[90:91], v[90:91], v[154:155]
	v_mov_b32_e32 v96, v1
	v_cvt_pk_fp8_f32 v96, v90, v91
	v_pk_add_f32 v[92:93], v[92:93], v[156:157]
	v_lshl_add_u64 v[102:103], v[98:99], 1, s[62:63]
	v_lshl_add_u64 v[98:99], s[64:65], 0, v[98:99]
	v_cvt_pk_fp8_f32 v96, v92, v93 op_sel:[0,0,1]
	s_mov_b64 exec, s[100:101]
	v_mov_b32_e32 v228, v94
	v_mov_b32_e32 v229, v95
	v_mov_b32_e32 v244, v105
	s_mov_b64 exec, -1
	v_mul_f32_e32 v94, v91, v91
	global_store_dwordx4 v[100:101], v[90:93], off offset:64
	v_fmac_f32_e32 v94, v90, v90
	v_mul_f32_e32 v95, v93, v93
	v_cvt_pk_bf16_f32 v90, v90, v91
	v_cvt_pk_bf16_f32 v91, v92, v93
	v_pk_add_f32 v[88:89], v[88:89], v[152:153]
	v_pk_add_f32 v[86:87], v[86:87], v[150:151]
	v_fmac_f32_e32 v95, v92, v92
	s_mov_b64 exec, s[100:101]
	v_mov_b32_e32 v230, v90
	v_mov_b32_e32 v231, v91
	v_lshl_add_u64 v[236:237], v[102:103], 0, v[202:203]
	s_nop 0
	v_permlane16_swap_b32_e32 v228, v230
	v_permlane16_swap_b32_e32 v229, v231
	global_store_dwordx4 v[236:237], v[228:231], off
	s_nop 1
	v_mov_b32_e32 v245, v96
	v_lshl_add_u64 v[238:239], v[98:99], 0, v[204:205]
	s_nop 0
	v_permlane16_swap_b32_e32 v244, v245
	global_store_dwordx2 v[238:239], v[244:245], off
	s_nop 0
	s_mov_b64 exec, -1
	v_mul_f32_e32 v90, v87, v87
	v_mul_f32_e32 v91, v89, v89
	v_add_f32_e32 v104, v104, v106
	v_add_f32_e32 v94, v94, v95
	v_fmac_f32_e32 v90, v86, v86
	v_fmac_f32_e32 v91, v88, v88
	v_add_f32_e32 v94, v104, v94
	v_add_f32_e32 v90, v90, v91
	v_mov_b32_e32 v92, v1
	global_store_dwordx4 v[100:101], v[86:89], off offset:512
	v_cvt_pk_fp8_f32 v92, v86, v87
	v_add_f32_e32 v93, v94, v90
	v_cvt_pk_bf16_f32 v90, v86, v87
	v_pk_add_f32 v[86:87], v[84:85], v[144:145]
	v_pk_add_f32 v[84:85], v[82:83], v[142:143]
	v_mul_f32_e32 v83, v87, v87
	v_mul_f32_e32 v82, v85, v85
	v_fmac_f32_e32 v82, v84, v84
	v_fmac_f32_e32 v83, v86, v86
	v_add_f32_e32 v82, v82, v83
	v_add_f32_e32 v82, v93, v82
	ds_bpermute_b32 v83, v242, v82
	v_cvt_pk_bf16_f32 v91, v88, v89
	v_cvt_pk_fp8_f32 v92, v88, v89 op_sel:[0,0,1]
	v_mov_b32_e32 v88, v1
	v_cvt_pk_fp8_f32 v88, v84, v85
	s_waitcnt lgkmcnt(0)
	v_add_f32_e32 v82, v82, v83
	ds_bpermute_b32 v83, v241, v82
	s_mov_b64 exec, s[100:101]
	v_mov_b32_e32 v232, v90
	v_mov_b32_e32 v233, v91
	v_mov_b32_e32 v246, v92
	s_mov_b64 exec, -1
	global_store_dwordx4 v[100:101], v[84:87], off offset:576
	v_cvt_pk_fp8_f32 v88, v86, v87 op_sel:[0,0,1]
	s_nop 0
	v_cvt_pk_bf16_f32 v84, v84, v85
	v_cvt_pk_bf16_f32 v85, v86, v87
	s_mov_b64 exec, s[100:101]
	v_mov_b32_e32 v234, v84
	v_mov_b32_e32 v235, v85
	v_lshl_add_u64 v[236:237], v[102:103], 0, v[202:203]
	s_nop 0
	v_permlane16_swap_b32_e32 v232, v234
	v_permlane16_swap_b32_e32 v233, v235
	global_store_dwordx4 v[236:237], v[232:235], off offset:256
	s_nop 1
	v_mov_b32_e32 v247, v88
	v_lshl_add_u64 v[238:239], v[98:99], 0, v[204:205]
	s_nop 0
	v_permlane16_swap_b32_e32 v246, v247
	global_store_dwordx2 v[238:239], v[246:247], off offset:128
	s_nop 0
	s_mov_b64 exec, -1
	s_and_saveexec_b64 s[66:67], vcc
	s_cbranch_execz .LBB0_422
	v_lshlrev_b32_e32 v84, 5, v214
	v_ashrrev_i32_e32 v85, 31, v84
	v_lshl_add_u64 v[84:85], v[84:85], 2, s[58:59]
	s_waitcnt lgkmcnt(0)
	v_add_f32_e32 v82, v82, v83
	global_store_dword v[84:85], v82, off
.LBB0_422:
	s_or_b64 exec, exec, s[66:67]
	v_pk_add_f32 v[78:79], v[78:79], v[146:147]
	v_mov_b32_e32 v89, v1
	v_cvt_pk_fp8_f32 v89, v78, v79
	s_waitcnt lgkmcnt(0)
	v_lshlrev_b64 v[82:83], 11, v[212:213]
	v_lshl_add_u64 v[82:83], v[82:83], 0, v[192:193]
	v_pk_add_f32 v[80:81], v[80:81], v[148:149]
	v_lshl_add_u64 v[84:85], v[82:83], 2, s[60:61]
	v_mul_f32_e32 v88, v79, v79
	v_mul_f32_e32 v90, v81, v81
	global_store_dwordx4 v[84:85], v[78:81], off
	v_fmac_f32_e32 v88, v78, v78
	v_fmac_f32_e32 v90, v80, v80
	v_cvt_pk_fp8_f32 v89, v80, v81 op_sel:[0,0,1]
	v_cvt_pk_bf16_f32 v78, v78, v79
	v_cvt_pk_bf16_f32 v79, v80, v81
	v_pk_add_f32 v[74:75], v[74:75], v[138:139]
	v_mov_b32_e32 v80, v1
	v_cvt_pk_fp8_f32 v80, v74, v75
	v_pk_add_f32 v[76:77], v[76:77], v[140:141]
	v_lshl_add_u64 v[86:87], v[82:83], 1, s[62:63]
	v_lshl_add_u64 v[82:83], s[64:65], 0, v[82:83]
	v_cvt_pk_fp8_f32 v80, v76, v77 op_sel:[0,0,1]
	s_mov_b64 exec, s[100:101]
	v_mov_b32_e32 v228, v78
	v_mov_b32_e32 v229, v79
	v_mov_b32_e32 v244, v89
	s_mov_b64 exec, -1
	v_mul_f32_e32 v78, v75, v75
	global_store_dwordx4 v[84:85], v[74:77], off offset:64
	v_fmac_f32_e32 v78, v74, v74
	v_mul_f32_e32 v79, v77, v77
	v_cvt_pk_bf16_f32 v74, v74, v75
	v_cvt_pk_bf16_f32 v75, v76, v77
	v_pk_add_f32 v[72:73], v[72:73], v[136:137]
	v_pk_add_f32 v[70:71], v[70:71], v[134:135]
	v_fmac_f32_e32 v79, v76, v76
	s_mov_b64 exec, s[100:101]
	v_mov_b32_e32 v230, v74
	v_mov_b32_e32 v231, v75
	v_lshl_add_u64 v[236:237], v[86:87], 0, v[202:203]
	s_nop 0
	v_permlane16_swap_b32_e32 v228, v230
	v_permlane16_swap_b32_e32 v229, v231
	global_store_dwordx4 v[236:237], v[228:231], off
	s_nop 1
	v_mov_b32_e32 v245, v80
	v_lshl_add_u64 v[238:239], v[82:83], 0, v[204:205]
	s_nop 0
	v_permlane16_swap_b32_e32 v244, v245
	global_store_dwordx2 v[238:239], v[244:245], off
	s_nop 0
	s_mov_b64 exec, -1
	v_mul_f32_e32 v74, v71, v71
	v_mul_f32_e32 v75, v73, v73
	v_add_f32_e32 v88, v88, v90
	v_add_f32_e32 v78, v78, v79
	v_fmac_f32_e32 v74, v70, v70
	v_fmac_f32_e32 v75, v72, v72
	v_add_f32_e32 v78, v88, v78
	v_add_f32_e32 v74, v74, v75
	v_mov_b32_e32 v76, v1
	global_store_dwordx4 v[84:85], v[70:73], off offset:512
	v_cvt_pk_fp8_f32 v76, v70, v71
	v_add_f32_e32 v77, v78, v74
	v_cvt_pk_bf16_f32 v74, v70, v71
	v_pk_add_f32 v[70:71], v[68:69], v[128:129]
	v_pk_add_f32 v[68:69], v[66:67], v[126:127]
	v_mul_f32_e32 v67, v71, v71
	v_mul_f32_e32 v66, v69, v69
	v_fmac_f32_e32 v66, v68, v68
	v_fmac_f32_e32 v67, v70, v70
	v_add_f32_e32 v66, v66, v67
	v_add_f32_e32 v66, v77, v66
	ds_bpermute_b32 v67, v242, v66
	v_cvt_pk_bf16_f32 v75, v72, v73
	v_cvt_pk_fp8_f32 v76, v72, v73 op_sel:[0,0,1]
	v_mov_b32_e32 v72, v1
	v_cvt_pk_fp8_f32 v72, v68, v69
	s_waitcnt lgkmcnt(0)
	v_add_f32_e32 v66, v66, v67
	ds_bpermute_b32 v67, v241, v66
	s_mov_b64 exec, s[100:101]
	v_mov_b32_e32 v232, v74
	v_mov_b32_e32 v233, v75
	v_mov_b32_e32 v246, v76
	s_mov_b64 exec, -1
	global_store_dwordx4 v[84:85], v[68:71], off offset:576
	v_cvt_pk_fp8_f32 v72, v70, v71 op_sel:[0,0,1]
	s_nop 0
	v_cvt_pk_bf16_f32 v68, v68, v69
	v_cvt_pk_bf16_f32 v69, v70, v71
	s_mov_b64 exec, s[100:101]
	v_mov_b32_e32 v234, v68
	v_mov_b32_e32 v235, v69
	v_lshl_add_u64 v[236:237], v[86:87], 0, v[202:203]
	s_nop 0
	v_permlane16_swap_b32_e32 v232, v234
	v_permlane16_swap_b32_e32 v233, v235
	global_store_dwordx4 v[236:237], v[232:235], off offset:256
	s_nop 1
	v_mov_b32_e32 v247, v72
	v_lshl_add_u64 v[238:239], v[82:83], 0, v[204:205]
	s_nop 0
	v_permlane16_swap_b32_e32 v246, v247
	global_store_dwordx2 v[238:239], v[246:247], off offset:128
	s_nop 0
	s_mov_b64 exec, -1
	s_and_saveexec_b64 s[66:67], vcc
	s_cbranch_execz .LBB0_424
	v_lshlrev_b32_e32 v68, 5, v212
	v_ashrrev_i32_e32 v69, 31, v68
	v_lshl_add_u64 v[68:69], v[68:69], 2, s[58:59]
	s_waitcnt lgkmcnt(0)
	v_add_f32_e32 v66, v66, v67
	global_store_dword v[68:69], v66, off
.LBB0_424:
	s_or_b64 exec, exec, s[66:67]
	v_add_u32_e32 v128, 0x80, v210
	v_ashrrev_i32_e32 v129, 31, v128
	s_waitcnt lgkmcnt(0)
	v_lshlrev_b64 v[66:67], 13, v[128:129]
	v_lshl_add_u64 v[66:67], v[208:209], 0, v[66:67]
	flat_load_dwordx4 v[136:139], v[66:67]
	flat_load_dwordx4 v[140:143], v[66:67] offset:64
	flat_load_dwordx4 v[118:121], v[66:67] offset:512
	flat_load_dwordx4 v[114:117], v[66:67] offset:576
	v_add_u32_e32 v126, 0x90, v210
	v_ashrrev_i32_e32 v127, 31, v126
	v_lshlrev_b64 v[66:67], 13, v[126:127]
	v_add_u32_e32 v124, 0xa0, v210
	v_lshl_add_u64 v[66:67], v[208:209], 0, v[66:67]
	v_ashrrev_i32_e32 v125, 31, v124
	flat_load_dwordx4 v[110:113], v[66:67]
	flat_load_dwordx4 v[106:109], v[66:67] offset:64
	flat_load_dwordx4 v[102:105], v[66:67] offset:512
	flat_load_dwordx4 v[98:101], v[66:67] offset:576
	v_lshlrev_b64 v[66:67], 13, v[124:125]
	v_add_u32_e32 v122, 0xb0, v210
	v_lshl_add_u64 v[66:67], v[208:209], 0, v[66:67]
	v_ashrrev_i32_e32 v123, 31, v122
	flat_load_dwordx4 v[94:97], v[66:67]
	flat_load_dwordx4 v[90:93], v[66:67] offset:64
	flat_load_dwordx4 v[86:89], v[66:67] offset:512
	flat_load_dwordx4 v[78:81], v[66:67] offset:576
	v_lshlrev_b64 v[66:67], 13, v[122:123]
	v_lshl_add_u64 v[66:67], v[208:209], 0, v[66:67]
	flat_load_dwordx4 v[82:85], v[66:67]
	flat_load_dwordx4 v[74:77], v[66:67] offset:64
	flat_load_dwordx4 v[70:73], v[66:67] offset:512
	s_nop 0
	flat_load_dwordx4 v[66:69], v[66:67] offset:576
	v_lshlrev_b64 v[130:131], 11, v[128:129]
	v_lshl_add_u64 v[130:131], v[130:131], 0, v[192:193]
	v_lshl_add_u64 v[134:135], v[130:131], 2, s[60:61]
	v_lshl_add_u64 v[132:133], v[130:131], 1, s[62:63]
	v_lshl_add_u64 v[130:131], s[64:65], 0, v[130:131]
	s_waitcnt vmcnt(0) lgkmcnt(0)
	v_pk_add_f32 v[64:65], v[64:65], v[138:139]
	v_pk_add_f32 v[62:63], v[62:63], v[136:137]
	v_mul_f32_e32 v136, v65, v65
	v_mul_f32_e32 v129, v63, v63
	v_fmac_f32_e32 v129, v62, v62
	v_fmac_f32_e32 v136, v64, v64
	global_store_dwordx4 v[134:135], v[62:65], off
	v_add_f32_e32 v129, v129, v136
	v_cvt_pk_bf16_f32 v136, v62, v63
	v_cvt_pk_bf16_f32 v137, v64, v65
	s_mov_b64 exec, s[100:101]
	v_mov_b32_e32 v228, v136
	v_mov_b32_e32 v229, v137
	s_mov_b64 exec, -1
	v_mov_b32_e32 v136, v1
	v_cvt_pk_fp8_f32 v136, v62, v63
	v_pk_add_f32 v[60:61], v[60:61], v[142:143]
	v_pk_add_f32 v[58:59], v[58:59], v[140:141]
	v_mul_f32_e32 v63, v61, v61
	v_cvt_pk_fp8_f32 v136, v64, v65 op_sel:[0,0,1]
	v_mul_f32_e32 v62, v59, v59
	v_fmac_f32_e32 v62, v58, v58
	v_fmac_f32_e32 v63, v60, v60
	v_add_f32_e32 v62, v62, v63
	s_mov_b64 exec, s[100:101]
	v_mov_b32_e32 v244, v136
	s_mov_b64 exec, -1
	global_store_dwordx4 v[134:135], v[58:61], off offset:64
	v_add_f32_e32 v64, v129, v62
	v_cvt_pk_bf16_f32 v62, v58, v59
	v_cvt_pk_bf16_f32 v63, v60, v61
	s_mov_b64 exec, s[100:101]
	v_mov_b32_e32 v230, v62
	v_mov_b32_e32 v231, v63
	v_lshl_add_u64 v[236:237], v[132:133], 0, v[202:203]
	s_nop 0
	v_permlane16_swap_b32_e32 v228, v230
	v_permlane16_swap_b32_e32 v229, v231
	global_store_dwordx4 v[236:237], v[228:231], off
	s_nop 1
	s_mov_b64 exec, -1
	v_mov_b32_e32 v62, v1
	v_cvt_pk_fp8_f32 v62, v58, v59
	v_pk_add_f32 v[56:57], v[56:57], v[120:121]
	v_pk_add_f32 v[54:55], v[54:55], v[118:119]
	v_mul_f32_e32 v59, v57, v57
	v_cvt_pk_fp8_f32 v62, v60, v61 op_sel:[0,0,1]
	v_mul_f32_e32 v58, v55, v55
	v_fmac_f32_e32 v58, v54, v54
	v_fmac_f32_e32 v59, v56, v56
	v_add_f32_e32 v58, v58, v59
	s_mov_b64 exec, s[100:101]
	v_mov_b32_e32 v245, v62
	v_lshl_add_u64 v[238:239], v[130:131], 0, v[204:205]
	s_nop 0
	v_permlane16_swap_b32_e32 v244, v245
	global_store_dwordx2 v[238:239], v[244:245], off
	s_nop 0
	s_mov_b64 exec, -1
	global_store_dwordx4 v[134:135], v[54:57], off offset:512
	v_add_f32_e32 v60, v64, v58
	v_cvt_pk_bf16_f32 v58, v54, v55
	v_cvt_pk_bf16_f32 v59, v56, v57
	s_mov_b64 exec, s[100:101]
	v_mov_b32_e32 v232, v58
	v_mov_b32_e32 v233, v59
	s_mov_b64 exec, -1
	v_mov_b32_e32 v58, v1
	v_cvt_pk_fp8_f32 v58, v54, v55
	v_pk_add_f32 v[52:53], v[52:53], v[116:117]
	v_pk_add_f32 v[50:51], v[50:51], v[114:115]
	v_mul_f32_e32 v55, v53, v53
	v_cvt_pk_fp8_f32 v58, v56, v57 op_sel:[0,0,1]
	v_mul_f32_e32 v54, v51, v51
	v_fmac_f32_e32 v54, v50, v50
	v_fmac_f32_e32 v55, v52, v52
	v_add_f32_e32 v54, v54, v55
	s_mov_b64 exec, s[100:101]
	v_mov_b32_e32 v246, v58
	s_mov_b64 exec, -1
	global_store_dwordx4 v[134:135], v[50:53], off offset:576
	v_add_f32_e32 v56, v60, v54
	v_cvt_pk_bf16_f32 v54, v50, v51
	v_cvt_pk_bf16_f32 v55, v52, v53
	s_mov_b64 exec, s[100:101]
	v_mov_b32_e32 v234, v54
	v_mov_b32_e32 v235, v55
	v_lshl_add_u64 v[236:237], v[132:133], 0, v[202:203]
	s_nop 0
	v_permlane16_swap_b32_e32 v232, v234
	v_permlane16_swap_b32_e32 v233, v235
	global_store_dwordx4 v[236:237], v[232:235], off offset:256
	s_nop 1
	s_mov_b64 exec, -1
	v_mov_b32_e32 v54, v1
	v_cvt_pk_fp8_f32 v54, v50, v51
	ds_bpermute_b32 v50, v242, v56
	v_cvt_pk_fp8_f32 v54, v52, v53 op_sel:[0,0,1]
	s_waitcnt lgkmcnt(0)
	v_add_f32_e32 v50, v56, v50
	ds_bpermute_b32 v51, v241, v50
	s_mov_b64 exec, s[100:101]
	v_mov_b32_e32 v247, v54
	v_lshl_add_u64 v[238:239], v[130:131], 0, v[204:205]
	s_nop 0
	v_permlane16_swap_b32_e32 v246, v247
	global_store_dwordx2 v[238:239], v[246:247], off offset:128
	s_nop 0
	s_mov_b64 exec, -1
	s_and_saveexec_b64 s[66:67], vcc
	s_cbranch_execz .LBB0_426
	v_lshlrev_b32_e32 v52, 5, v128
	v_ashrrev_i32_e32 v53, 31, v52
	v_lshl_add_u64 v[52:53], v[52:53], 2, s[58:59]
	s_waitcnt lgkmcnt(0)
	v_add_f32_e32 v50, v50, v51
	global_store_dword v[52:53], v50, off
.LBB0_426:
	s_or_b64 exec, exec, s[66:67]
	v_pk_add_f32 v[46:47], v[46:47], v[110:111]
	v_mov_b32_e32 v57, v1
	v_cvt_pk_fp8_f32 v57, v46, v47
	s_waitcnt lgkmcnt(0)
	v_lshlrev_b64 v[50:51], 11, v[126:127]
	v_lshl_add_u64 v[50:51], v[50:51], 0, v[192:193]
	v_pk_add_f32 v[48:49], v[48:49], v[112:113]
	v_lshl_add_u64 v[52:53], v[50:51], 2, s[60:61]
	v_mul_f32_e32 v56, v47, v47
	v_mul_f32_e32 v58, v49, v49
	global_store_dwordx4 v[52:53], v[46:49], off
	v_fmac_f32_e32 v56, v46, v46
	v_fmac_f32_e32 v58, v48, v48
	v_cvt_pk_fp8_f32 v57, v48, v49 op_sel:[0,0,1]
	v_cvt_pk_bf16_f32 v46, v46, v47
	v_cvt_pk_bf16_f32 v47, v48, v49
	v_pk_add_f32 v[42:43], v[42:43], v[106:107]
	v_mov_b32_e32 v48, v1
	v_cvt_pk_fp8_f32 v48, v42, v43
	v_pk_add_f32 v[44:45], v[44:45], v[108:109]
	v_lshl_add_u64 v[54:55], v[50:51], 1, s[62:63]
	v_lshl_add_u64 v[50:51], s[64:65], 0, v[50:51]
	v_cvt_pk_fp8_f32 v48, v44, v45 op_sel:[0,0,1]
	s_mov_b64 exec, s[100:101]
	v_mov_b32_e32 v228, v46
	v_mov_b32_e32 v229, v47
	v_mov_b32_e32 v244, v57
	s_mov_b64 exec, -1
	v_mul_f32_e32 v46, v43, v43
	global_store_dwordx4 v[52:53], v[42:45], off offset:64
	v_fmac_f32_e32 v46, v42, v42
	v_mul_f32_e32 v47, v45, v45
	v_cvt_pk_bf16_f32 v42, v42, v43
	v_cvt_pk_bf16_f32 v43, v44, v45
	v_pk_add_f32 v[40:41], v[40:41], v[104:105]
	v_pk_add_f32 v[38:39], v[38:39], v[102:103]
	v_fmac_f32_e32 v47, v44, v44
	s_mov_b64 exec, s[100:101]
	v_mov_b32_e32 v230, v42
	v_mov_b32_e32 v231, v43
	v_lshl_add_u64 v[236:237], v[54:55], 0, v[202:203]
	s_nop 0
	v_permlane16_swap_b32_e32 v228, v230
	v_permlane16_swap_b32_e32 v229, v231
	global_store_dwordx4 v[236:237], v[228:231], off
	s_nop 1
	v_mov_b32_e32 v245, v48
	v_lshl_add_u64 v[238:239], v[50:51], 0, v[204:205]
	s_nop 0
	v_permlane16_swap_b32_e32 v244, v245
	global_store_dwordx2 v[238:239], v[244:245], off
	s_nop 0
	s_mov_b64 exec, -1
	v_mul_f32_e32 v42, v39, v39
	v_mul_f32_e32 v43, v41, v41
	v_add_f32_e32 v56, v56, v58
	v_add_f32_e32 v46, v46, v47
	v_fmac_f32_e32 v42, v38, v38
	v_fmac_f32_e32 v43, v40, v40
	v_add_f32_e32 v46, v56, v46
	v_add_f32_e32 v42, v42, v43
	v_mov_b32_e32 v44, v1
	global_store_dwordx4 v[52:53], v[38:41], off offset:512
	v_cvt_pk_fp8_f32 v44, v38, v39
	v_add_f32_e32 v45, v46, v42
	v_cvt_pk_bf16_f32 v42, v38, v39
	v_pk_add_f32 v[38:39], v[36:37], v[100:101]
	v_pk_add_f32 v[36:37], v[34:35], v[98:99]
	v_mul_f32_e32 v35, v39, v39
	v_mul_f32_e32 v34, v37, v37
	v_fmac_f32_e32 v34, v36, v36
	v_fmac_f32_e32 v35, v38, v38
	v_add_f32_e32 v34, v34, v35
	v_add_f32_e32 v34, v45, v34
	ds_bpermute_b32 v35, v242, v34
	v_cvt_pk_bf16_f32 v43, v40, v41
	v_cvt_pk_fp8_f32 v44, v40, v41 op_sel:[0,0,1]
	v_mov_b32_e32 v40, v1
	v_cvt_pk_fp8_f32 v40, v36, v37
	s_waitcnt lgkmcnt(0)
	v_add_f32_e32 v34, v34, v35
	ds_bpermute_b32 v35, v241, v34
	s_mov_b64 exec, s[100:101]
	v_mov_b32_e32 v232, v42
	v_mov_b32_e32 v233, v43
	v_mov_b32_e32 v246, v44
	s_mov_b64 exec, -1
	global_store_dwordx4 v[52:53], v[36:39], off offset:576
	v_cvt_pk_fp8_f32 v40, v38, v39 op_sel:[0,0,1]
	s_nop 0
	v_cvt_pk_bf16_f32 v36, v36, v37
	v_cvt_pk_bf16_f32 v37, v38, v39
	s_mov_b64 exec, s[100:101]
	v_mov_b32_e32 v234, v36
	v_mov_b32_e32 v235, v37
	v_lshl_add_u64 v[236:237], v[54:55], 0, v[202:203]
	s_nop 0
	v_permlane16_swap_b32_e32 v232, v234
	v_permlane16_swap_b32_e32 v233, v235
	global_store_dwordx4 v[236:237], v[232:235], off offset:256
	s_nop 1
	v_mov_b32_e32 v247, v40
	v_lshl_add_u64 v[238:239], v[50:51], 0, v[204:205]
	s_nop 0
	v_permlane16_swap_b32_e32 v246, v247
	global_store_dwordx2 v[238:239], v[246:247], off offset:128
	s_nop 0
	s_mov_b64 exec, -1
	s_and_saveexec_b64 s[66:67], vcc
	s_cbranch_execz .LBB0_428
	v_lshlrev_b32_e32 v36, 5, v126
	v_ashrrev_i32_e32 v37, 31, v36
	v_lshl_add_u64 v[36:37], v[36:37], 2, s[58:59]
	s_waitcnt lgkmcnt(0)
	v_add_f32_e32 v34, v34, v35
	global_store_dword v[36:37], v34, off
.LBB0_428:
	s_or_b64 exec, exec, s[66:67]
	v_pk_add_f32 v[30:31], v[30:31], v[94:95]
	v_mov_b32_e32 v41, v1
	v_cvt_pk_fp8_f32 v41, v30, v31
	s_waitcnt lgkmcnt(0)
	v_lshlrev_b64 v[34:35], 11, v[124:125]
	v_lshl_add_u64 v[34:35], v[34:35], 0, v[192:193]
	v_pk_add_f32 v[32:33], v[32:33], v[96:97]
	v_lshl_add_u64 v[36:37], v[34:35], 2, s[60:61]
	v_mul_f32_e32 v40, v31, v31
	v_mul_f32_e32 v42, v33, v33
	global_store_dwordx4 v[36:37], v[30:33], off
	v_fmac_f32_e32 v40, v30, v30
	v_fmac_f32_e32 v42, v32, v32
	v_cvt_pk_fp8_f32 v41, v32, v33 op_sel:[0,0,1]
	v_cvt_pk_bf16_f32 v30, v30, v31
	v_cvt_pk_bf16_f32 v31, v32, v33
	v_pk_add_f32 v[26:27], v[26:27], v[90:91]
	v_mov_b32_e32 v32, v1
	v_cvt_pk_fp8_f32 v32, v26, v27
	v_pk_add_f32 v[28:29], v[28:29], v[92:93]
	v_lshl_add_u64 v[38:39], v[34:35], 1, s[62:63]
	v_lshl_add_u64 v[34:35], s[64:65], 0, v[34:35]
	v_cvt_pk_fp8_f32 v32, v28, v29 op_sel:[0,0,1]
	s_mov_b64 exec, s[100:101]
	v_mov_b32_e32 v228, v30
	v_mov_b32_e32 v229, v31
	v_mov_b32_e32 v244, v41
	s_mov_b64 exec, -1
	v_mul_f32_e32 v30, v27, v27
	global_store_dwordx4 v[36:37], v[26:29], off offset:64
	v_fmac_f32_e32 v30, v26, v26
	v_mul_f32_e32 v31, v29, v29
	v_cvt_pk_bf16_f32 v26, v26, v27
	v_cvt_pk_bf16_f32 v27, v28, v29
	v_pk_add_f32 v[24:25], v[24:25], v[88:89]
	v_pk_add_f32 v[22:23], v[22:23], v[86:87]
	v_fmac_f32_e32 v31, v28, v28
	s_mov_b64 exec, s[100:101]
	v_mov_b32_e32 v230, v26
	v_mov_b32_e32 v231, v27
	v_lshl_add_u64 v[236:237], v[38:39], 0, v[202:203]
	s_nop 0
	v_permlane16_swap_b32_e32 v228, v230
	v_permlane16_swap_b32_e32 v229, v231
	global_store_dwordx4 v[236:237], v[228:231], off
	s_nop 1
	v_mov_b32_e32 v245, v32
	v_lshl_add_u64 v[238:239], v[34:35], 0, v[204:205]
	s_nop 0
	v_permlane16_swap_b32_e32 v244, v245
	global_store_dwordx2 v[238:239], v[244:245], off
	s_nop 0
	s_mov_b64 exec, -1
	v_mul_f32_e32 v26, v23, v23
	v_mul_f32_e32 v27, v25, v25
	v_add_f32_e32 v40, v40, v42
	v_add_f32_e32 v30, v30, v31
	v_fmac_f32_e32 v26, v22, v22
	v_fmac_f32_e32 v27, v24, v24
	v_add_f32_e32 v30, v40, v30
	v_add_f32_e32 v26, v26, v27
	v_mov_b32_e32 v28, v1
	global_store_dwordx4 v[36:37], v[22:25], off offset:512
	v_cvt_pk_fp8_f32 v28, v22, v23
	v_add_f32_e32 v29, v30, v26
	v_cvt_pk_bf16_f32 v26, v22, v23
	v_pk_add_f32 v[22:23], v[20:21], v[80:81]
	v_pk_add_f32 v[20:21], v[18:19], v[78:79]
	v_mul_f32_e32 v19, v23, v23
	v_mul_f32_e32 v18, v21, v21
	v_fmac_f32_e32 v18, v20, v20
	v_fmac_f32_e32 v19, v22, v22
	v_add_f32_e32 v18, v18, v19
	v_add_f32_e32 v18, v29, v18
	ds_bpermute_b32 v19, v242, v18
	v_cvt_pk_bf16_f32 v27, v24, v25
	v_cvt_pk_fp8_f32 v28, v24, v25 op_sel:[0,0,1]
	v_mov_b32_e32 v24, v1
	v_cvt_pk_fp8_f32 v24, v20, v21
	s_waitcnt lgkmcnt(0)
	v_add_f32_e32 v18, v18, v19
	ds_bpermute_b32 v19, v241, v18
	s_mov_b64 exec, s[100:101]
	v_mov_b32_e32 v232, v26
	v_mov_b32_e32 v233, v27
	v_mov_b32_e32 v246, v28
	s_mov_b64 exec, -1
	global_store_dwordx4 v[36:37], v[20:23], off offset:576
	v_cvt_pk_fp8_f32 v24, v22, v23 op_sel:[0,0,1]
	s_nop 0
	v_cvt_pk_bf16_f32 v20, v20, v21
	v_cvt_pk_bf16_f32 v21, v22, v23
	s_mov_b64 exec, s[100:101]
	v_mov_b32_e32 v234, v20
	v_mov_b32_e32 v235, v21
	v_lshl_add_u64 v[236:237], v[38:39], 0, v[202:203]
	s_nop 0
	v_permlane16_swap_b32_e32 v232, v234
	v_permlane16_swap_b32_e32 v233, v235
	global_store_dwordx4 v[236:237], v[232:235], off offset:256
	s_nop 1
	v_mov_b32_e32 v247, v24
	v_lshl_add_u64 v[238:239], v[34:35], 0, v[204:205]
	s_nop 0
	v_permlane16_swap_b32_e32 v246, v247
	global_store_dwordx2 v[238:239], v[246:247], off offset:128
	s_nop 0
	s_mov_b64 exec, -1
	s_and_saveexec_b64 s[66:67], vcc
	s_cbranch_execz .LBB0_430
	v_lshlrev_b32_e32 v20, 5, v124
	v_ashrrev_i32_e32 v21, 31, v20
	v_lshl_add_u64 v[20:21], v[20:21], 2, s[58:59]
	s_waitcnt lgkmcnt(0)
	v_add_f32_e32 v18, v18, v19
	global_store_dword v[20:21], v18, off
.LBB0_430:
	s_or_b64 exec, exec, s[66:67]
	v_pk_add_f32 v[14:15], v[14:15], v[82:83]
	v_mov_b32_e32 v25, v1
	v_cvt_pk_fp8_f32 v25, v14, v15
	s_waitcnt lgkmcnt(0)
	v_lshlrev_b64 v[18:19], 11, v[122:123]
	v_lshl_add_u64 v[18:19], v[18:19], 0, v[192:193]
	v_pk_add_f32 v[16:17], v[16:17], v[84:85]
	v_lshl_add_u64 v[20:21], v[18:19], 2, s[60:61]
	v_mul_f32_e32 v24, v15, v15
	v_mul_f32_e32 v26, v17, v17
	global_store_dwordx4 v[20:21], v[14:17], off
	v_fmac_f32_e32 v24, v14, v14
	v_fmac_f32_e32 v26, v16, v16
	v_cvt_pk_fp8_f32 v25, v16, v17 op_sel:[0,0,1]
	v_cvt_pk_bf16_f32 v14, v14, v15
	v_cvt_pk_bf16_f32 v15, v16, v17
	v_pk_add_f32 v[10:11], v[10:11], v[74:75]
	v_mov_b32_e32 v16, v1
	v_cvt_pk_fp8_f32 v16, v10, v11
	v_pk_add_f32 v[12:13], v[12:13], v[76:77]
	v_lshl_add_u64 v[22:23], v[18:19], 1, s[62:63]
	v_lshl_add_u64 v[18:19], s[64:65], 0, v[18:19]
	v_cvt_pk_fp8_f32 v16, v12, v13 op_sel:[0,0,1]
	s_mov_b64 exec, s[100:101]
	v_mov_b32_e32 v228, v14
	v_mov_b32_e32 v229, v15
	v_mov_b32_e32 v244, v25
	s_mov_b64 exec, -1
	v_mul_f32_e32 v14, v11, v11
	global_store_dwordx4 v[20:21], v[10:13], off offset:64
	v_fmac_f32_e32 v14, v10, v10
	v_mul_f32_e32 v15, v13, v13
	v_cvt_pk_bf16_f32 v10, v10, v11
	v_cvt_pk_bf16_f32 v11, v12, v13
	v_pk_add_f32 v[8:9], v[8:9], v[72:73]
	v_pk_add_f32 v[6:7], v[6:7], v[70:71]
	v_fmac_f32_e32 v15, v12, v12
	s_mov_b64 exec, s[100:101]
	v_mov_b32_e32 v230, v10
	v_mov_b32_e32 v231, v11
	v_lshl_add_u64 v[236:237], v[22:23], 0, v[202:203]
	s_nop 0
	v_permlane16_swap_b32_e32 v228, v230
	v_permlane16_swap_b32_e32 v229, v231
	global_store_dwordx4 v[236:237], v[228:231], off
	s_nop 1
	v_mov_b32_e32 v245, v16
	v_lshl_add_u64 v[238:239], v[18:19], 0, v[204:205]
	s_nop 0
	v_permlane16_swap_b32_e32 v244, v245
	global_store_dwordx2 v[238:239], v[244:245], off
	s_nop 0
	s_mov_b64 exec, -1
	v_mul_f32_e32 v10, v7, v7
	v_mul_f32_e32 v11, v9, v9
	v_add_f32_e32 v24, v24, v26
	v_add_f32_e32 v14, v14, v15
	v_fmac_f32_e32 v10, v6, v6
	v_fmac_f32_e32 v11, v8, v8
	v_add_f32_e32 v14, v24, v14
	v_add_f32_e32 v10, v10, v11
	v_mov_b32_e32 v12, v1
	global_store_dwordx4 v[20:21], v[6:9], off offset:512
	v_cvt_pk_fp8_f32 v12, v6, v7
	v_add_f32_e32 v13, v14, v10
	v_cvt_pk_bf16_f32 v10, v6, v7
	v_pk_add_f32 v[6:7], v[4:5], v[68:69]
	v_pk_add_f32 v[4:5], v[2:3], v[66:67]
	v_mul_f32_e32 v3, v7, v7
	v_mul_f32_e32 v2, v5, v5
	v_fmac_f32_e32 v2, v4, v4
	v_fmac_f32_e32 v3, v6, v6
	v_add_f32_e32 v2, v2, v3
	v_add_f32_e32 v2, v13, v2
	ds_bpermute_b32 v3, v242, v2
	v_cvt_pk_bf16_f32 v11, v8, v9
	v_cvt_pk_fp8_f32 v12, v8, v9 op_sel:[0,0,1]
	v_mov_b32_e32 v8, v1
	v_cvt_pk_fp8_f32 v8, v4, v5
	s_waitcnt lgkmcnt(0)
	v_add_f32_e32 v2, v2, v3
	ds_bpermute_b32 v3, v241, v2
	s_mov_b64 exec, s[100:101]
	v_mov_b32_e32 v232, v10
	v_mov_b32_e32 v233, v11
	v_mov_b32_e32 v246, v12
	s_mov_b64 exec, -1
	global_store_dwordx4 v[20:21], v[4:7], off offset:576
	v_cvt_pk_fp8_f32 v8, v6, v7 op_sel:[0,0,1]
	s_nop 0
	v_cvt_pk_bf16_f32 v4, v4, v5
	v_cvt_pk_bf16_f32 v5, v6, v7
	s_mov_b64 exec, s[100:101]
	v_mov_b32_e32 v234, v4
	v_mov_b32_e32 v235, v5
	v_lshl_add_u64 v[236:237], v[22:23], 0, v[202:203]
	s_nop 0
	v_permlane16_swap_b32_e32 v232, v234
	v_permlane16_swap_b32_e32 v233, v235
	global_store_dwordx4 v[236:237], v[232:235], off offset:256
	s_nop 1
	v_mov_b32_e32 v247, v8
	v_lshl_add_u64 v[238:239], v[18:19], 0, v[204:205]
	s_nop 0
	v_permlane16_swap_b32_e32 v246, v247
	global_store_dwordx2 v[238:239], v[246:247], off offset:128
	s_nop 0
	s_mov_b64 exec, -1
	s_and_saveexec_b64 s[60:61], vcc
	s_cbranch_execz .LBB0_432
	v_lshlrev_b32_e32 v4, 5, v122
	v_ashrrev_i32_e32 v5, 31, v4
	v_lshl_add_u64 v[4:5], v[4:5], 2, s[58:59]
	s_waitcnt lgkmcnt(0)
	v_add_f32_e32 v2, v2, v3
	global_store_dword v[4:5], v2, off
